# P4: workgroups with index bit 3 set start the phase 10 us late (s_sleep) so the grid's compute-bound mainloops and bandwidth-bound gate epilogues are out of phase
# baseline (speedup 1.0000x reference)
.LBB0_419:
	s_or_b64 exec, exec, s[0:1]
	s_mov_b32 s4, s92
	s_mov_b32 s54, s90
	v_readlane_b32 s0, v254, 3
	s_waitcnt lgkmcnt(0)
	s_barrier
	s_bitcmp1_b32 s4, 3
	s_cbranch_scc0 .Ld4_skip
	s_sleep 127
	s_sleep 127
	s_sleep 127
.Ld4_skip:
	v_mbcnt_lo_u32_b32 v0, -1, 0
	v_mbcnt_hi_u32_b32 v0, -1, v0
	s_nop 0
	v_or_b32_e32 v2, s0, v0
	s_nop 0
	v_ashrrev_i32_e32 v4, 8, v2
	v_cmp_lt_i32_e32 vcc, 7, v4
	s_and_saveexec_b64 s[2:3], vcc
	s_xor_b64 s[6:7], exec, s[2:3]
	s_ashr_i32 s5, s4, 31
	s_lshl_b64 s[0:1], s[4:5], 14
	s_or_saveexec_b64 s[6:7], s[6:7]
	v_mov_b64_e32 v[160:161], s[4:5]
	v_mov_b64_e32 v[0:1], s[0:1]
	s_xor_b64 exec, exec, s[6:7]
	s_cbranch_execz .LBB0_433
	s_ashr_i32 s5, s4, 31
	v_ashrrev_i32_e32 v5, 31, v4
	s_lshl_b64 s[12:13], s[4:5], 14
	v_lshlrev_b64 v[0:1], 11, v[4:5]
	v_and_b32_e32 v6, 0xff, v2
	v_lshl_add_u64 v[0:1], s[12:13], 0, v[0:1]
	v_lshl_or_b32 v0, v6, 3, v0
	v_lshl_add_u64 v[0:1], s[88:89], 0, v[0:1]
	s_mov_b64 s[0:1], 0x2300000
	s_ashr_i32 s55, s54, 31
	v_add_u32_e32 v7, -2, v4
	v_lshl_add_u64 v[2:3], v[0:1], 0, s[0:1]
	v_mad_i64_i32 v[0:1], s[0:1], s54, v4, 0
	v_add_u32_e32 v8, s4, v0
	s_lshl_b32 s2, s54, 1
	s_lshl_b64 s[38:39], s[54:55], 1
	v_mad_i64_i32 v[4:5], s[0:1], v7, s54, 0
	s_mov_b64 s[42:43], 0
	s_mov_b64 s[44:45], 0x200
	s_mov_b64 s[46:47], 0x1000
	s_mov_b32 s52, 0x3a800000
	s_mov_b32 s3, 0x800000
	s_mov_b64 s[56:57], s[4:5]
	s_branch .LBB0_424
